# weight-conversion items run by idle workgroups: the 32 norm-gain loads issued together (were 32 serialized load+wait pairs)
# speedup vs baseline: 1.0242x; 1.0058x over previous
.LBB0_819:
	v_lshlrev_b32_e32 v6, 6, v6
	v_or_b32_e32 v72, v6, v75
	v_ashrrev_i32_e32 v73, 31, v72
	v_or_b32_e32 v12, 4, v72
	v_ashrrev_i32_e32 v9, 31, v8
	v_mul_lo_u32 v7, v73, s14
	v_mad_u64_u32 v[12:13], s[18:19], v12, s14, 0
	v_lshl_add_u64 v[64:65], v[8:9], 2, v[2:3]
	v_add_u32_e32 v13, v13, v7
	v_or_b32_e32 v10, 2, v72
	v_lshl_add_u64 v[16:17], v[12:13], 2, v[64:65]
	v_or_b32_e32 v12, 6, v72
	v_mad_u64_u32 v[8:9], s[18:19], v72, s14, 0
	v_mad_u64_u32 v[10:11], s[18:19], v10, s14, 0
	v_mad_u64_u32 v[12:13], s[18:19], v12, s14, 0
	v_or_b32_e32 v20, 12, v72
	v_add_u32_e32 v9, v9, v7
	v_add_u32_e32 v11, v11, v7
	v_add_u32_e32 v13, v13, v7
	v_mad_u64_u32 v[20:21], s[18:19], v20, s14, 0
	v_lshl_add_u64 v[8:9], v[8:9], 2, v[64:65]
	v_lshl_add_u64 v[10:11], v[10:11], 2, v[64:65]
	v_lshl_add_u64 v[18:19], v[12:13], 2, v[64:65]
	v_add_u32_e32 v21, v21, v7
	global_load_dwordx2 v[14:15], v[8:9], off
	global_load_dwordx2 v[12:13], v[10:11], off
	s_nop 0
	global_load_dwordx2 v[10:11], v[16:17], off
	global_load_dwordx2 v[8:9], v[18:19], off
	v_or_b32_e32 v16, 8, v72
	v_or_b32_e32 v18, 10, v72
	v_lshl_add_u64 v[24:25], v[20:21], 2, v[64:65]
	v_or_b32_e32 v20, 14, v72
	v_mad_u64_u32 v[16:17], s[18:19], v16, s14, 0
	v_mad_u64_u32 v[18:19], s[18:19], v18, s14, 0
	v_mad_u64_u32 v[20:21], s[18:19], v20, s14, 0
	v_or_b32_e32 v28, 20, v72
	v_add_u32_e32 v17, v17, v7
	v_add_u32_e32 v19, v19, v7
	v_add_u32_e32 v21, v21, v7
	v_mad_u64_u32 v[28:29], s[18:19], v28, s14, 0
	v_lshl_add_u64 v[16:17], v[16:17], 2, v[64:65]
	v_lshl_add_u64 v[18:19], v[18:19], 2, v[64:65]
	v_lshl_add_u64 v[26:27], v[20:21], 2, v[64:65]
	v_add_u32_e32 v29, v29, v7
	global_load_dwordx2 v[22:23], v[16:17], off
	global_load_dwordx2 v[20:21], v[18:19], off
	s_nop 0
	global_load_dwordx2 v[18:19], v[24:25], off
	global_load_dwordx2 v[16:17], v[26:27], off
	v_or_b32_e32 v24, 16, v72
	v_or_b32_e32 v26, 18, v72
	v_lshl_add_u64 v[32:33], v[28:29], 2, v[64:65]
	v_or_b32_e32 v28, 22, v72
	v_mad_u64_u32 v[24:25], s[18:19], v24, s14, 0
	v_mad_u64_u32 v[26:27], s[18:19], v26, s14, 0
	v_mad_u64_u32 v[28:29], s[18:19], v28, s14, 0
	v_or_b32_e32 v36, 28, v72
	v_add_u32_e32 v25, v25, v7
	v_add_u32_e32 v27, v27, v7
	v_add_u32_e32 v29, v29, v7
	v_mad_u64_u32 v[36:37], s[18:19], v36, s14, 0
	v_lshl_add_u64 v[24:25], v[24:25], 2, v[64:65]
	v_lshl_add_u64 v[26:27], v[26:27], 2, v[64:65]
	v_lshl_add_u64 v[34:35], v[28:29], 2, v[64:65]
	v_add_u32_e32 v37, v37, v7
	global_load_dwordx2 v[30:31], v[24:25], off
	global_load_dwordx2 v[28:29], v[26:27], off
	s_nop 0
	global_load_dwordx2 v[26:27], v[32:33], off
	global_load_dwordx2 v[24:25], v[34:35], off
	v_or_b32_e32 v32, 24, v72
	v_or_b32_e32 v34, 26, v72
	v_lshl_add_u64 v[40:41], v[36:37], 2, v[64:65]
	v_or_b32_e32 v36, 30, v72
	v_mad_u64_u32 v[32:33], s[18:19], v32, s14, 0
	v_mad_u64_u32 v[34:35], s[18:19], v34, s14, 0
	v_mad_u64_u32 v[36:37], s[18:19], v36, s14, 0
	v_or_b32_e32 v44, 36, v72
	v_add_u32_e32 v33, v33, v7
	v_add_u32_e32 v35, v35, v7
	v_add_u32_e32 v37, v37, v7
	v_mad_u64_u32 v[44:45], s[18:19], v44, s14, 0
	v_lshl_add_u64 v[32:33], v[32:33], 2, v[64:65]
	v_lshl_add_u64 v[34:35], v[34:35], 2, v[64:65]
	v_lshl_add_u64 v[42:43], v[36:37], 2, v[64:65]
	v_add_u32_e32 v45, v45, v7
	global_load_dwordx2 v[38:39], v[32:33], off
	global_load_dwordx2 v[36:37], v[34:35], off
	s_nop 0
	global_load_dwordx2 v[34:35], v[40:41], off
	global_load_dwordx2 v[32:33], v[42:43], off
	v_or_b32_e32 v40, 32, v72
	v_or_b32_e32 v42, 34, v72
	v_lshl_add_u64 v[48:49], v[44:45], 2, v[64:65]
	v_or_b32_e32 v44, 38, v72
	v_mad_u64_u32 v[40:41], s[18:19], v40, s14, 0
	v_mad_u64_u32 v[42:43], s[18:19], v42, s14, 0
	v_mad_u64_u32 v[44:45], s[18:19], v44, s14, 0
	v_or_b32_e32 v52, 44, v72
	v_add_u32_e32 v41, v41, v7
	v_add_u32_e32 v43, v43, v7
	v_add_u32_e32 v45, v45, v7
	v_mad_u64_u32 v[52:53], s[18:19], v52, s14, 0
	v_lshl_add_u64 v[40:41], v[40:41], 2, v[64:65]
	v_lshl_add_u64 v[42:43], v[42:43], 2, v[64:65]
	v_lshl_add_u64 v[50:51], v[44:45], 2, v[64:65]
	v_add_u32_e32 v53, v53, v7
	global_load_dwordx2 v[46:47], v[40:41], off
	global_load_dwordx2 v[44:45], v[42:43], off
	s_nop 0
	global_load_dwordx2 v[42:43], v[48:49], off
	global_load_dwordx2 v[40:41], v[50:51], off
	v_or_b32_e32 v48, 40, v72
	v_or_b32_e32 v50, 42, v72
	v_lshl_add_u64 v[56:57], v[52:53], 2, v[64:65]
	v_or_b32_e32 v52, 46, v72
	v_mad_u64_u32 v[48:49], s[18:19], v48, s14, 0
	v_mad_u64_u32 v[50:51], s[18:19], v50, s14, 0
	v_mad_u64_u32 v[52:53], s[18:19], v52, s14, 0
	v_or_b32_e32 v60, 52, v72
	v_add_u32_e32 v49, v49, v7
	v_add_u32_e32 v51, v51, v7
	v_add_u32_e32 v53, v53, v7
	v_mad_u64_u32 v[60:61], s[18:19], v60, s14, 0
	v_lshl_add_u64 v[48:49], v[48:49], 2, v[64:65]
	v_lshl_add_u64 v[50:51], v[50:51], 2, v[64:65]
	v_lshl_add_u64 v[58:59], v[52:53], 2, v[64:65]
	v_add_u32_e32 v61, v61, v7
	global_load_dwordx2 v[54:55], v[48:49], off
	global_load_dwordx2 v[52:53], v[50:51], off
	s_nop 0
	global_load_dwordx2 v[50:51], v[56:57], off
	global_load_dwordx2 v[48:49], v[58:59], off
	v_or_b32_e32 v56, 48, v72
	v_or_b32_e32 v58, 50, v72
	v_lshl_add_u64 v[66:67], v[60:61], 2, v[64:65]
	v_or_b32_e32 v60, 54, v72
	v_mad_u64_u32 v[56:57], s[18:19], v56, s14, 0
	v_mad_u64_u32 v[58:59], s[18:19], v58, s14, 0
	v_mad_u64_u32 v[60:61], s[18:19], v60, s14, 0
	v_or_b32_e32 v70, 60, v72
	v_add_u32_e32 v57, v57, v7
	v_add_u32_e32 v59, v59, v7
	v_add_u32_e32 v61, v61, v7
	v_mad_u64_u32 v[70:71], s[18:19], v70, s14, 0
	v_lshl_add_u64 v[56:57], v[56:57], 2, v[64:65]
	v_lshl_add_u64 v[58:59], v[58:59], 2, v[64:65]
	v_lshl_add_u64 v[68:69], v[60:61], 2, v[64:65]
	v_add_u32_e32 v71, v71, v7
	global_load_dwordx2 v[62:63], v[56:57], off
	global_load_dwordx2 v[60:61], v[58:59], off
	s_nop 0
	global_load_dwordx2 v[58:59], v[66:67], off
	global_load_dwordx2 v[56:57], v[68:69], off
	v_or_b32_e32 v66, 56, v72
	v_or_b32_e32 v68, 58, v72
	v_lshl_add_u64 v[90:91], v[70:71], 2, v[64:65]
	v_or_b32_e32 v70, 62, v72
	v_mad_u64_u32 v[66:67], s[18:19], v66, s14, 0
	v_mad_u64_u32 v[68:69], s[18:19], v68, s14, 0
	v_mad_u64_u32 v[70:71], s[18:19], v70, s14, 0
	v_add_u32_e32 v67, v67, v7
	v_add_u32_e32 v69, v69, v7
	v_add_u32_e32 v71, v71, v7
	v_lshl_add_u64 v[66:67], v[66:67], 2, v[64:65]
	v_lshl_add_u64 v[68:69], v[68:69], 2, v[64:65]
	v_lshl_add_u64 v[64:65], v[70:71], 2, v[64:65]
	global_load_dwordx2 v[70:71], v[66:67], off
	s_nop 0
	global_load_dwordx2 v[68:69], v[68:69], off
	s_nop 0
	global_load_dwordx2 v[66:67], v[90:91], off
	s_nop 0
	global_load_dwordx2 v[64:65], v[64:65], off
	s_andn2_b64 vcc, exec, s[16:17]
	s_cbranch_vccnz .LBB0_816
	v_lshl_add_u64 v[72:73], v[72:73], 2, s[4:5]
	global_load_dword v128, v[72:73], off
	global_load_dword v129, v[72:73], off offset:8
	global_load_dword v130, v[72:73], off offset:16
	global_load_dword v131, v[72:73], off offset:24
	global_load_dword v132, v[72:73], off offset:32
	global_load_dword v133, v[72:73], off offset:40
	global_load_dword v134, v[72:73], off offset:48
	global_load_dword v135, v[72:73], off offset:56
	global_load_dword v136, v[72:73], off offset:64
	global_load_dword v137, v[72:73], off offset:72
	global_load_dword v138, v[72:73], off offset:80
	global_load_dword v139, v[72:73], off offset:88
	global_load_dword v140, v[72:73], off offset:96
	global_load_dword v141, v[72:73], off offset:104
	global_load_dword v142, v[72:73], off offset:112
	global_load_dword v143, v[72:73], off offset:120
	global_load_dword v144, v[72:73], off offset:128
	global_load_dword v145, v[72:73], off offset:136
	global_load_dword v146, v[72:73], off offset:144
	global_load_dword v147, v[72:73], off offset:152
	global_load_dword v148, v[72:73], off offset:160
	global_load_dword v149, v[72:73], off offset:168
	global_load_dword v150, v[72:73], off offset:176
	global_load_dword v151, v[72:73], off offset:184
	global_load_dword v152, v[72:73], off offset:192
	global_load_dword v153, v[72:73], off offset:200
	global_load_dword v154, v[72:73], off offset:208
	global_load_dword v155, v[72:73], off offset:216
	global_load_dword v170, v[72:73], off offset:224
	global_load_dword v171, v[72:73], off offset:232
	global_load_dword v172, v[72:73], off offset:240
	global_load_dword v173, v[72:73], off offset:248
	s_waitcnt vmcnt(0)
	v_pk_mul_f32 v[14:15], v[14:15], v[128:129] op_sel_hi:[1,0]
	v_pk_mul_f32 v[12:13], v[12:13], v[128:129] op_sel:[0,1] op_sel_hi:[1,1]
	v_pk_mul_f32 v[10:11], v[10:11], v[130:131] op_sel_hi:[1,0]
	v_pk_mul_f32 v[8:9], v[8:9], v[130:131] op_sel:[0,1] op_sel_hi:[1,1]
	v_pk_mul_f32 v[22:23], v[22:23], v[132:133] op_sel_hi:[1,0]
	v_pk_mul_f32 v[20:21], v[20:21], v[132:133] op_sel:[0,1] op_sel_hi:[1,1]
	v_pk_mul_f32 v[18:19], v[18:19], v[134:135] op_sel_hi:[1,0]
	v_pk_mul_f32 v[16:17], v[16:17], v[134:135] op_sel:[0,1] op_sel_hi:[1,1]
	v_pk_mul_f32 v[30:31], v[30:31], v[136:137] op_sel_hi:[1,0]
	v_pk_mul_f32 v[28:29], v[28:29], v[136:137] op_sel:[0,1] op_sel_hi:[1,1]
	v_pk_mul_f32 v[26:27], v[26:27], v[138:139] op_sel_hi:[1,0]
	v_pk_mul_f32 v[24:25], v[24:25], v[138:139] op_sel:[0,1] op_sel_hi:[1,1]
	v_pk_mul_f32 v[38:39], v[38:39], v[140:141] op_sel_hi:[1,0]
	v_pk_mul_f32 v[36:37], v[36:37], v[140:141] op_sel:[0,1] op_sel_hi:[1,1]
	v_pk_mul_f32 v[34:35], v[34:35], v[142:143] op_sel_hi:[1,0]
	v_pk_mul_f32 v[32:33], v[32:33], v[142:143] op_sel:[0,1] op_sel_hi:[1,1]
	v_pk_mul_f32 v[46:47], v[46:47], v[144:145] op_sel_hi:[1,0]
	v_pk_mul_f32 v[44:45], v[44:45], v[144:145] op_sel:[0,1] op_sel_hi:[1,1]
	v_pk_mul_f32 v[42:43], v[42:43], v[146:147] op_sel_hi:[1,0]
	v_pk_mul_f32 v[40:41], v[40:41], v[146:147] op_sel:[0,1] op_sel_hi:[1,1]
	v_pk_mul_f32 v[54:55], v[54:55], v[148:149] op_sel_hi:[1,0]
	v_pk_mul_f32 v[52:53], v[52:53], v[148:149] op_sel:[0,1] op_sel_hi:[1,1]
	v_pk_mul_f32 v[50:51], v[50:51], v[150:151] op_sel_hi:[1,0]
	v_pk_mul_f32 v[48:49], v[48:49], v[150:151] op_sel:[0,1] op_sel_hi:[1,1]
	v_pk_mul_f32 v[62:63], v[62:63], v[152:153] op_sel_hi:[1,0]
	v_pk_mul_f32 v[60:61], v[60:61], v[152:153] op_sel:[0,1] op_sel_hi:[1,1]
	v_pk_mul_f32 v[58:59], v[58:59], v[154:155] op_sel_hi:[1,0]
	v_pk_mul_f32 v[56:57], v[56:57], v[154:155] op_sel:[0,1] op_sel_hi:[1,1]
	v_pk_mul_f32 v[70:71], v[70:71], v[170:171] op_sel_hi:[1,0]
	v_pk_mul_f32 v[68:69], v[68:69], v[170:171] op_sel:[0,1] op_sel_hi:[1,1]
	v_pk_mul_f32 v[66:67], v[66:67], v[172:173] op_sel_hi:[1,0]
	v_pk_mul_f32 v[64:65], v[64:65], v[172:173] op_sel:[0,1] op_sel_hi:[1,1]
	s_branch .LBB0_816
